# hg epilogue: row sum-of-squares exchange without the two ds_bpermute round trips (8 partials per row summed after the barrier)
# speedup vs baseline: 1.0092x; 1.0092x over previous
; __device__ __forceinline__ unsigned cvt_pk_bf16(float lo, float hi) { unsigned r; asm("v_cvt_pk_bf16_f32 %0, %1, %2" : "=v"(r) : "v"(lo), "v"(hi)); return r; }
; template <int DK, int DV, bool SEPQ> ...
;     ...
;         for (int vt = 0; vt < NVT; ++vt) { const f32x4 s = S[ct][vt]; u32x2 w; w.x = cvt_pk_bf16(s[0], s[1]); w.y = cvt_pk_bf16(s[2], s[3]);
;             *(u32x2*)(ST + (16 * vt + fr) * LQ + 16 * (wid * NCTW + ct) + 4 * fq) = w; }
;     __syncthreads();
;     {
;         const float gi_i = GI[16 * m + fr];
;         const int n0 = 2 * hw, n1 = 2 * hw + 1; const bool do0 = n0 <= m, do1 = n1 <= m;
;         f32x4 acc0 = {0.f, 0.f, 0.f, 0.f}, acc1 = {0.f, 0.f, 0.f, 0.f};
; #pragma unroll
;         for (int vt = 0; vt < NVTW; ++vt) O[vt] = (f32x4){0.f, 0.f, 0.f, 0.f};
; #pragma unroll
;         for (int ks = 0; ks < DK / 32; ++ks) {
;             const bf16x8 qf = *(const bf16x8*)(QA + (16 * m + fr) * LQ + 32 * ks + 8 * fq);
;             if (do0) { const bf16x8 kf = *(const bf16x8*)(KB + (16 * n0 + fr) * LQ + 32 * ks + 8 * fq); acc0 = __builtin_amdgcn_mfma_f32_16x16x32_bf16(kf, qf, acc0, 0, 0, 0); }
;             if (do1) { const bf16x8 kf = *(const bf16x8*)(KB + (16 * n1 + fr) * LQ + 32 * ks + 8 * fq); acc1 = __builtin_amdgcn_mfma_f32_16x16x32_bf16(kf, qf, acc1, 0, 0, 0); }
;             bf16x8 qs = qf; if (SEPQ) qs = *(const bf16x8*)(QS + (16 * m + fr) * LQ + 32 * ks + 8 * fq);
; #pragma unroll
;             for (int vt = 0; vt < NVTW; ++vt) { const bf16x8 sf = *(const bf16x8*)(ST + (16 * (hw * NVTW + vt) + fr) * LQ + 32 * ks + 8 * fq); O[vt] = __builtin_amdgcn_mfma_f32_16x16x32_bf16(sf, qs, O[vt], 0, 0, 0); }
;         }
; #pragma unroll
;         for (int nn = 0; nn < 2; ++nn) {
;             const int n = 2 * hw + nn; const f32x4 acc = nn == 0 ? acc0 : acc1;
;             const f32x4 gj = *(const f32x4*)(GI + 16 * n + 4 * fq); const int i = 16 * m + fr, j0 = 16 * n + 4 * fq; float p[4];
; #pragma unroll
;             for (int e = 0; e < 4; ++e) p[e] = (j0 + e <= i) ? acc[e] * __expf(gi_i - gj[e]) : 0.f;
;             u32x2 w; w.x = cvt_pk_bf16(p[0], p[1]); w.y = cvt_pk_bf16(p[2], p[3]); *(u32x2*)(P + (16 * m + fr) * LJ + j0) = w;
;         }
;         const float ei = __expf(gi_i);
; #pragma unroll
;         for (int vt = 0; vt < NVTW; ++vt) O[vt] = O[vt] * ei;
.LBB0_420:
	s_lshl_b32 s54, s62, 9
	s_mov_b32 s55, s12
	v_lshl_add_u64 v[218:219], v[114:115], 0, s[54:55]
	global_load_dwordx4 v[202:205], v[218:219], off
	global_load_dwordx4 v[206:209], v[218:219], off offset:64
	global_load_dwordx4 v[210:213], v[218:219], off offset:128
	global_load_dwordx4 v[214:217], v[218:219], off offset:192
	v_cvt_pk_bf16_f32 v50, v18, v19
	v_cvt_pk_bf16_f32 v51, v20, v21
	ds_write_b64 v169, v[50:51]
	v_cvt_pk_bf16_f32 v50, v22, v23
	v_cvt_pk_bf16_f32 v51, v24, v25
	ds_write_b64 v169, v[50:51] offset:4352
	v_cvt_pk_bf16_f32 v50, v26, v27
	v_cvt_pk_bf16_f32 v51, v28, v29
	ds_write_b64 v169, v[50:51] offset:8704
	v_cvt_pk_bf16_f32 v50, v30, v31
	v_cvt_pk_bf16_f32 v51, v32, v33
	ds_write_b64 v169, v[50:51] offset:13056
	v_cvt_pk_bf16_f32 v50, v34, v35
	v_cvt_pk_bf16_f32 v51, v36, v37
	ds_write_b64 v169, v[50:51] offset:17408
	v_cvt_pk_bf16_f32 v50, v38, v39
	v_cvt_pk_bf16_f32 v51, v40, v41
	ds_write_b64 v169, v[50:51] offset:21760
	v_cvt_pk_bf16_f32 v50, v42, v43
	v_cvt_pk_bf16_f32 v51, v44, v45
	ds_write_b64 v169, v[50:51] offset:26112
	v_cvt_pk_bf16_f32 v50, v46, v47
	v_cvt_pk_bf16_f32 v51, v48, v49
	ds_write_b64 v169, v[50:51] offset:30464
	s_waitcnt lgkmcnt(0)
	s_barrier
	ds_read_b32 v16, v138
	ds_read_b128 v[218:221], v139
	ds_read_b128 v[222:225], v140 offset:17408
	ds_read_b128 v[226:229], v140 offset:21760
	ds_read_b128 v[242:245], v139 offset:34816
	ds_read_b128 v[246:249], v174
	ds_read_b128 v[74:77], v174 offset:4352
	ds_read_b128 v[176:179], v174 offset:8704
	ds_read_b128 v[180:183], v174 offset:13056
	ds_read_b128 v[230:233], v139 offset:64
	ds_read_b128 v[234:237], v140 offset:17472
	ds_read_b128 v[238:241], v140 offset:21824
	s_waitcnt lgkmcnt(8)
	v_mfma_f32_16x16x32_bf16 v[54:57], v[222:225], v[218:221], 0
	v_mfma_f32_16x16x32_bf16 v[50:53], v[226:229], v[218:221], 0
	s_waitcnt lgkmcnt(3)
	v_mfma_f32_16x16x32_bf16 v[58:61], v[246:249], v[242:245], 0
	v_mfma_f32_16x16x32_bf16 v[62:65], v[74:77], v[242:245], 0
	v_mfma_f32_16x16x32_bf16 v[66:69], v[176:179], v[242:245], 0
	v_mfma_f32_16x16x32_bf16 v[70:73], v[180:183], v[242:245], 0
	ds_read_b128 v[242:245], v139 offset:34880
	ds_read_b128 v[246:249], v174 offset:64
	ds_read_b128 v[74:77], v174 offset:4416
	ds_read_b128 v[176:179], v174 offset:8768
	ds_read_b128 v[180:183], v174 offset:13120
	ds_read_b128 v[218:221], v139 offset:128
	ds_read_b128 v[222:225], v140 offset:17536
	ds_read_b128 v[226:229], v140 offset:21888
	s_waitcnt lgkmcnt(8)
	v_mfma_f32_16x16x32_bf16 v[54:57], v[234:237], v[230:233], v[54:57]
	v_mfma_f32_16x16x32_bf16 v[50:53], v[238:241], v[230:233], v[50:53]
	s_waitcnt lgkmcnt(3)
	v_mfma_f32_16x16x32_bf16 v[58:61], v[246:249], v[242:245], v[58:61]
	v_mfma_f32_16x16x32_bf16 v[62:65], v[74:77], v[242:245], v[62:65]
	v_mfma_f32_16x16x32_bf16 v[66:69], v[176:179], v[242:245], v[66:69]
	v_mfma_f32_16x16x32_bf16 v[70:73], v[180:183], v[242:245], v[70:73]
	ds_read_b128 v[242:245], v139 offset:34944
	ds_read_b128 v[246:249], v174 offset:128
	ds_read_b128 v[74:77], v174 offset:4480
	ds_read_b128 v[176:179], v174 offset:8832
	ds_read_b128 v[180:183], v174 offset:13184
	ds_read_b128 v[230:233], v139 offset:192
	ds_read_b128 v[234:237], v140 offset:17600
	ds_read_b128 v[238:241], v140 offset:21952
	s_waitcnt lgkmcnt(8)
	v_mfma_f32_16x16x32_bf16 v[54:57], v[222:225], v[218:221], v[54:57]
	v_mfma_f32_16x16x32_bf16 v[50:53], v[226:229], v[218:221], v[50:53]
	s_waitcnt lgkmcnt(3)
	v_mfma_f32_16x16x32_bf16 v[58:61], v[246:249], v[242:245], v[58:61]
	v_mfma_f32_16x16x32_bf16 v[62:65], v[74:77], v[242:245], v[62:65]
	v_mfma_f32_16x16x32_bf16 v[66:69], v[176:179], v[242:245], v[66:69]
	v_mfma_f32_16x16x32_bf16 v[70:73], v[180:183], v[242:245], v[70:73]
	ds_read_b128 v[242:245], v139 offset:35008
	ds_read_b128 v[246:249], v174 offset:192
	ds_read_b128 v[74:77], v174 offset:4544
	ds_read_b128 v[176:179], v174 offset:8896
	ds_read_b128 v[180:183], v174 offset:13248
	s_waitcnt lgkmcnt(5)
	v_mfma_f32_16x16x32_bf16 v[54:57], v[234:237], v[230:233], v[54:57]
	v_mfma_f32_16x16x32_bf16 v[50:53], v[238:241], v[230:233], v[50:53]
	s_waitcnt lgkmcnt(0)
	v_mfma_f32_16x16x32_bf16 v[58:61], v[246:249], v[242:245], v[58:61]
	v_mfma_f32_16x16x32_bf16 v[62:65], v[74:77], v[242:245], v[62:65]
	v_mfma_f32_16x16x32_bf16 v[66:69], v[176:179], v[242:245], v[66:69]
	v_mfma_f32_16x16x32_bf16 v[70:73], v[180:183], v[242:245], v[70:73]
	s_nop 7
	v_readlane_b32 s52, v255, 14
	v_readlane_b32 s53, v255, 15
	ds_read_b128 v[74:77], v141
	s_waitcnt lgkmcnt(0)
	v_sub_f32_e32 v74, v16, v74
	v_mul_f32_e32 v74, 0x3fb8aa3b, v74
	v_exp_f32_e32 v74, v74
	s_nop 0
	v_mul_f32_e32 v54, v54, v74
	v_sub_f32_e32 v74, v16, v75
	v_mul_f32_e32 v74, 0x3fb8aa3b, v74
	v_exp_f32_e32 v74, v74
	v_cndmask_b32_e64 v54, v54, 0, s[52:53]
	v_readlane_b32 s52, v255, 16
	v_readlane_b32 s53, v255, 17
	v_mul_f32_e32 v55, v55, v74
	v_sub_f32_e32 v74, v16, v76
	v_mul_f32_e32 v74, 0x3fb8aa3b, v74
	v_exp_f32_e32 v74, v74
	v_cndmask_b32_e64 v55, 0, v55, s[52:53]
	v_readlane_b32 s52, v255, 18
	v_readlane_b32 s53, v255, 19
	v_mul_f32_e32 v56, v56, v74
	v_sub_f32_e32 v74, v16, v77
	v_mul_f32_e32 v74, 0x3fb8aa3b, v74
	v_exp_f32_e32 v74, v74
	v_cndmask_b32_e64 v56, v56, 0, s[52:53]
	v_readlane_b32 s52, v255, 20
	v_readlane_b32 s53, v255, 21
	v_mul_f32_e32 v57, v57, v74
	v_cvt_pk_bf16_f32 v54, v54, v55
	s_nop 0
	v_cndmask_b32_e64 v57, v57, 0, s[52:53]
	v_cvt_pk_bf16_f32 v55, v56, v57
	ds_write_b64 v142, v[54:55]
	ds_read_b128 v[54:57], v141 offset:64
	v_readlane_b32 s52, v255, 22
	v_readlane_b32 s53, v255, 23
	s_waitcnt lgkmcnt(0)
	v_sub_f32_e32 v54, v16, v54
	v_mul_f32_e32 v54, 0x3fb8aa3b, v54
	v_exp_f32_e32 v54, v54
	s_nop 0
	v_mul_f32_e32 v50, v50, v54
	v_sub_f32_e32 v54, v16, v55
	v_mul_f32_e32 v54, 0x3fb8aa3b, v54
	v_exp_f32_e32 v54, v54
	v_cndmask_b32_e64 v50, v50, 0, s[52:53]
	v_readlane_b32 s52, v255, 24
	v_readlane_b32 s53, v255, 25
	v_mul_f32_e32 v51, v51, v54
	v_sub_f32_e32 v54, v16, v56
	v_mul_f32_e32 v54, 0x3fb8aa3b, v54
	v_exp_f32_e32 v54, v54
	v_cndmask_b32_e64 v51, 0, v51, s[52:53]
	v_readlane_b32 s52, v255, 26
	v_readlane_b32 s53, v255, 27
	v_mul_f32_e32 v52, v52, v54
	v_sub_f32_e32 v54, v16, v57
	v_mul_f32_e32 v54, 0x3fb8aa3b, v54
	v_exp_f32_e32 v54, v54
	v_mul_f32_e32 v16, 0x3fb8aa3b, v16
	v_exp_f32_e32 v16, v16
	v_cndmask_b32_e64 v52, v52, 0, s[52:53]
	v_readlane_b32 s52, v255, 28
	v_mul_f32_e32 v53, v53, v54
	v_readlane_b32 s53, v255, 29
	v_cvt_pk_bf16_f32 v50, v50, v51
	v_pk_mul_f32 v[54:55], v[16:17], v[62:63] op_sel_hi:[0,1]
	v_pk_mul_f32 v[56:57], v[16:17], v[64:65] op_sel_hi:[0,1]
	v_cndmask_b32_e64 v53, v53, 0, s[52:53]
	v_cvt_pk_bf16_f32 v51, v52, v53
	ds_write_b64 v142, v[50:51] offset:32
	v_pk_mul_f32 v[50:51], v[16:17], v[58:59] op_sel_hi:[0,1]
	v_pk_mul_f32 v[52:53], v[16:17], v[60:61] op_sel_hi:[0,1]
	v_pk_mul_f32 v[58:59], v[16:17], v[66:67] op_sel_hi:[0,1]
	v_pk_mul_f32 v[60:61], v[16:17], v[68:69] op_sel_hi:[0,1]
	v_pk_mul_f32 v[62:63], v[16:17], v[70:71] op_sel_hi:[0,1]
	v_pk_mul_f32 v[64:65], v[16:17], v[72:73] op_sel_hi:[0,1]
	s_waitcnt lgkmcnt(0)
	s_barrier
; template <int DK, int DV, bool SEPQ> ...
;     ...
; #pragma unroll
;     for (int ks = 0; ks < 2; ++ks) { const bf16x8 pf = *(const bf16x8*)(P + (16 * m + fr) * LJ + 32 * ks + 8 * fq);
; #pragma unroll
;         for (int vt = 0; vt < NVTW; ++vt) { const bf16x8 vf = *(const bf16x8*)(VT + (16 * (hw * NVTW + vt) + fr) * LJ + 32 * ks + 8 * fq); O[vt] = __builtin_amdgcn_mfma_f32_16x16x32_bf16(vf, pf, O[vt], 0, 0, 0); } }
; #pragma unroll
;     for (int ct = 0; ct < NCTW; ++ct) { const int ctg = wid * NCTW + ct; const f32x4 dec = *(const f32x4*)(SDEC + 16 * ctg + 4 * fq);
; #pragma unroll
;         for (int vt = 0; vt < NVT; ++vt) S[ct][vt] = S[ct][vt] * dec;
; #pragma unroll
;         for (int ks = 0; ks < 2; ++ks) { const bf16x8 kf = *(const bf16x8*)(KT + (16 * ctg + fr) * LJ + 32 * ks + 8 * fq);
; #pragma unroll
;             for (int vt = 0; vt < NVT; ++vt) { const bf16x8 vf = *(const bf16x8*)(VT2 + (16 * vt + fr) * LJ + 32 * ks + 8 * fq); S[ct][vt] = __builtin_amdgcn_mfma_f32_16x16x32_bf16(kf, vf, S[ct][vt], 0, 0, 0); } } }
; __device__ __forceinline__ void hg_block(ArgsP a_, int jl, unsigned char* smem) { const ArgsP a = a_;
;     ...
;         { float ss = 0.f;
; #pragma unroll
;           for (int vt = 0; vt < 4; ++vt) ss += (O[vt][0] * O[vt][0] + O[vt][1] * O[vt][1]) + (O[vt][2] * O[vt][2] + O[vt][3] * O[vt][3]);
;           ss += __shfl_xor(ss, 16); ss += __shfl_xor(ss, 32); if (fq == 0) RSm[irow * 2 + hw] = ss; }
	ds_read_b128 v[218:221], v143
	ds_read_b128 v[222:225], v143 offset:64
	ds_read_b128 v[226:229], v184
	ds_read_b128 v[230:233], v185 offset:2304
	ds_read_b128 v[234:237], v184 offset:4608
	ds_read_b128 v[238:241], v185 offset:6912
	ds_read_b128 v[242:245], v184 offset:64
	ds_read_b128 v[246:249], v185 offset:2368
	ds_read_b128 v[74:77], v184 offset:4672
	ds_read_b128 v[176:179], v185 offset:6976
	s_waitcnt lgkmcnt(7)
	v_mfma_f32_16x16x32_bf16 v[50:53], v[226:229], v[218:221], v[50:53]
	s_waitcnt lgkmcnt(6)
	v_mfma_f32_16x16x32_bf16 v[54:57], v[230:233], v[218:221], v[54:57]
	s_waitcnt lgkmcnt(5)
	v_mfma_f32_16x16x32_bf16 v[70:73], v[234:237], v[218:221], v[58:61]
	s_waitcnt lgkmcnt(4)
	v_mfma_f32_16x16x32_bf16 v[66:69], v[238:241], v[218:221], v[62:65]
	s_waitcnt lgkmcnt(3)
	v_mfma_f32_16x16x32_bf16 v[62:65], v[242:245], v[222:225], v[50:53]
	s_waitcnt lgkmcnt(2)
	v_mfma_f32_16x16x32_bf16 v[58:61], v[246:249], v[222:225], v[54:57]
	s_waitcnt lgkmcnt(1)
	v_mfma_f32_16x16x32_bf16 v[54:57], v[74:77], v[222:225], v[70:73]
	s_waitcnt lgkmcnt(0)
	v_mfma_f32_16x16x32_bf16 v[50:53], v[176:179], v[222:225], v[66:69]
	ds_read_b128 v[180:183], v171
	ds_read_b128 v[74:77], v144 offset:52224
	ds_read_b128 v[176:179], v144 offset:52288
	ds_read_b128 v[218:221], v250
	ds_read_b128 v[222:225], v251 offset:2304
	ds_read_b128 v[226:229], v250 offset:4608
	ds_read_b128 v[230:233], v251 offset:6912
	ds_read_b128 v[234:237], v250 offset:9216
	ds_read_b128 v[238:241], v251 offset:11520
	ds_read_b128 v[242:245], v250 offset:13824
	ds_read_b128 v[246:249], v251 offset:16128
	s_waitcnt lgkmcnt(10)
	v_pk_mul_f32 v[18:19], v[18:19], v[180:181]
	v_pk_mul_f32 v[20:21], v[20:21], v[182:183]
	v_pk_mul_f32 v[22:23], v[22:23], v[180:181]
	v_pk_mul_f32 v[24:25], v[24:25], v[182:183]
	v_pk_mul_f32 v[26:27], v[26:27], v[180:181]
	v_pk_mul_f32 v[28:29], v[28:29], v[182:183]
	v_pk_mul_f32 v[30:31], v[30:31], v[180:181]
	v_pk_mul_f32 v[32:33], v[32:33], v[182:183]
	v_pk_mul_f32 v[34:35], v[34:35], v[180:181]
	v_pk_mul_f32 v[36:37], v[36:37], v[182:183]
	v_pk_mul_f32 v[38:39], v[38:39], v[180:181]
	v_pk_mul_f32 v[40:41], v[40:41], v[182:183]
	v_pk_mul_f32 v[42:43], v[42:43], v[180:181]
	v_pk_mul_f32 v[44:45], v[44:45], v[182:183]
	v_pk_mul_f32 v[46:47], v[46:47], v[180:181]
	v_pk_mul_f32 v[48:49], v[48:49], v[182:183]
	v_mul_f32_e32 v16, v63, v63
	v_fmac_f32_e32 v16, v62, v62
	ds_read_b128 v[66:69], v250 offset:64
	ds_read_b128 v[70:73], v251 offset:2368
	s_waitcnt lgkmcnt(9)
	v_mfma_f32_16x16x32_bf16 v[18:21], v[74:77], v[218:221], v[18:21]
	ds_read_b128 v[218:221], v250 offset:4672
	s_waitcnt lgkmcnt(9)
	v_mfma_f32_16x16x32_bf16 v[22:25], v[74:77], v[222:225], v[22:25]
	ds_read_b128 v[222:225], v251 offset:6976
	s_waitcnt lgkmcnt(9)
	v_mfma_f32_16x16x32_bf16 v[26:29], v[74:77], v[226:229], v[26:29]
	ds_read_b128 v[226:229], v250 offset:9280
	s_waitcnt lgkmcnt(9)
	v_mfma_f32_16x16x32_bf16 v[30:33], v[74:77], v[230:233], v[30:33]
	ds_read_b128 v[230:233], v251 offset:11584
	s_waitcnt lgkmcnt(9)
	v_mfma_f32_16x16x32_bf16 v[34:37], v[74:77], v[234:237], v[34:37]
	ds_read_b128 v[234:237], v250 offset:13888
	s_waitcnt lgkmcnt(9)
	v_mfma_f32_16x16x32_bf16 v[38:41], v[74:77], v[238:241], v[38:41]
	ds_read_b128 v[238:241], v251 offset:16192
	s_waitcnt lgkmcnt(9)
	v_mfma_f32_16x16x32_bf16 v[42:45], v[74:77], v[242:245], v[42:45]
	s_waitcnt lgkmcnt(8)
	v_mfma_f32_16x16x32_bf16 v[46:49], v[74:77], v[246:249], v[46:49]
	s_waitcnt lgkmcnt(7)
	v_mfma_f32_16x16x32_bf16 v[18:21], v[176:179], v[66:69], v[18:21]
	s_waitcnt lgkmcnt(6)
	v_mfma_f32_16x16x32_bf16 v[22:25], v[176:179], v[70:73], v[22:25]
	s_waitcnt lgkmcnt(5)
	v_mfma_f32_16x16x32_bf16 v[26:29], v[176:179], v[218:221], v[26:29]
	s_waitcnt lgkmcnt(4)
	v_mfma_f32_16x16x32_bf16 v[30:33], v[176:179], v[222:225], v[30:33]
	s_waitcnt lgkmcnt(3)
	v_mfma_f32_16x16x32_bf16 v[34:37], v[176:179], v[226:229], v[34:37]
	s_waitcnt lgkmcnt(2)
	v_mfma_f32_16x16x32_bf16 v[38:41], v[176:179], v[230:233], v[38:41]
	s_waitcnt lgkmcnt(1)
	v_mfma_f32_16x16x32_bf16 v[42:45], v[176:179], v[234:237], v[42:45]
	s_waitcnt lgkmcnt(0)
	v_mfma_f32_16x16x32_bf16 v[46:49], v[176:179], v[238:241], v[46:49]
	s_nop 7
	v_mul_f32_e32 v66, v65, v65
	v_fmac_f32_e32 v66, v64, v64
	v_add_f32_e32 v16, v16, v66
	v_mul_f32_e32 v66, v59, v59
	v_mul_f32_e32 v67, v61, v61
	v_fmac_f32_e32 v66, v58, v58
	v_fmac_f32_e32 v67, v60, v60
	v_add_f32_e32 v66, v66, v67
	v_add_f32_e32 v16, v16, v66
	v_mul_f32_e32 v66, v55, v55
	v_mul_f32_e32 v67, v57, v57
	v_fmac_f32_e32 v66, v54, v54
	v_fmac_f32_e32 v67, v56, v56
	v_add_f32_e32 v66, v66, v67
	v_add_f32_e32 v16, v16, v66
	v_mul_f32_e32 v66, v51, v51
	v_mul_f32_e32 v67, v53, v53
	v_fmac_f32_e32 v66, v50, v50
	v_fmac_f32_e32 v67, v52, v52
	v_add_f32_e32 v66, v66, v67
	v_add_f32_e32 v16, v16, v66
	v_subrev_u32_e32 v66, 0x22b00, v173
	v_lshrrev_b32_e32 v67, 2, v188
	v_and_b32_e32 v67, 12, v67
	v_lshl_add_u32 v66, v66, 2, v67
	v_add_u32_e32 v66, 0x22b00, v66
	ds_write_b32 v66, v16
; __device__ __forceinline__ unsigned cvt_pk_bf16(float lo, float hi) { unsigned r; asm("v_cvt_pk_bf16_f32 %0, %1, %2" : "=v"(r) : "v"(lo), "v"(hi)); return r; }
; __device__ __forceinline__ void hg_block(ArgsP a_, int jl, unsigned char* smem) { const ArgsP a = a_;
;     ...
;         __syncthreads();
;         if (irow < len) { const float rstd = rsqrtf((RSm[irow * 2] + RSm[irow * 2 + 1]) * (1.f / 128.f) + LN_EPS);
; #pragma unroll
;             for (int vt = 0; vt < 4; ++vt) { const int v = 16 * (hw * 4 + vt) + 4 * fq; const size_t o = (size_t)(row0 + irow) * 1024 + h * 128 + v;
;                 const f32x4 gg = *(const f32x4*)(ng + h * 128 + v); const u32x2 gt = gcur[vt];
;                 const float g0 = __uint_as_float(gt.x << 16), g1 = __uint_as_float(gt.x & 0xffff0000u), g2 = __uint_as_float(gt.y << 16), g3 = __uint_as_float(gt.y & 0xffff0000u);
;                 u32x2 w; w.x = cvt_pk_bf16(O[vt][0] * rstd * gg[0] * g0, O[vt][1] * rstd * gg[1] * g1); w.y = cvt_pk_bf16(O[vt][2] * rstd * gg[2] * g2, O[vt][3] * rstd * gg[3] * g3);
;                 *(u32x2*)(ON + o) = w; } }
.LBB0_438:
	v_cmp_gt_i32_e32 vcc, s64, v134
	s_waitcnt lgkmcnt(0)
	s_barrier
	s_and_saveexec_b64 s[52:53], vcc
	s_cbranch_execz .Lhg_epi_skip
	v_lshlrev_b32_e32 v16, 2, v145
	v_add_u32_e32 v16, 0x22b00, v16
	ds_read_b128 v[218:221], v16
	ds_read_b128 v[222:225], v16 offset:16
	s_lshl_b32 s54, s62, 8
	v_readlane_b32 s55, v255, 8
	s_add_u32 s54, s55, s54
	v_readlane_b32 s55, v255, 9
	s_waitcnt lgkmcnt(0)
	v_add_f32_e32 v218, v218, v219
	v_add_f32_e32 v220, v220, v221
	v_add_f32_e32 v222, v222, v223
	v_add_f32_e32 v224, v224, v225
	v_add_f32_e32 v218, v218, v220
	v_add_f32_e32 v222, v222, v224
	v_add_f32_e32 v16, v218, v222
	v_fmamk_f32 v16, v16, 0x3c000000, v187
	v_cmp_gt_f32_e32 vcc, s31, v16
	v_mul_f32_e32 v66, 0x4b800000, v16
	s_addc_u32 s55, s55, 0
	v_cndmask_b32_e32 v16, v16, v66, vcc
	v_rsq_f32_e32 v16, v16
	v_lshlrev_b32_e32 v74, 16, v124
	v_and_b32_e32 v75, 0xffff0000, v124
	v_lshlrev_b32_e32 v76, 16, v125
	v_mul_f32_e32 v66, 0x45800000, v16
	v_cndmask_b32_e32 v16, v16, v66, vcc
	v_add_u32_e32 v66, s63, v134
	v_ashrrev_i32_e32 v67, 31, v66
	v_lshlrev_b64 v[66:67], 11, v[66:67]
	v_lshl_add_u64 v[72:73], s[54:55], 0, v[66:67]
	s_lshl_b32 s54, s62, 9
	s_mov_b32 s55, s12
	v_lshl_add_u64 v[66:67], v[114:115], 0, s[54:55]
	v_mul_f32_e32 v62, v62, v16
	v_mul_f32_e32 v63, v63, v16
	v_and_b32_e32 v77, 0xffff0000, v125
	v_mov_b32_e32 v123, v17
	v_mul_f32_e32 v58, v58, v16
	v_mul_f32_e32 v59, v59, v16
	v_mul_f32_e32 v54, v54, v16
	v_mul_f32_e32 v55, v55, v16
	v_mul_f32_e32 v50, v50, v16
	v_mul_f32_e32 v51, v51, v16
	s_waitcnt vmcnt(0)
	v_mul_f32_e32 v62, v202, v62
	v_mul_f32_e32 v63, v203, v63
	v_mul_f32_e32 v62, v62, v74
	v_mul_f32_e32 v63, v63, v75
	v_cvt_pk_bf16_f32 v68, v62, v63
	v_mul_f32_e32 v62, v64, v16
	v_mul_f32_e32 v63, v65, v16
	v_mul_f32_e32 v62, v204, v62
	v_mul_f32_e32 v63, v205, v63
	v_mul_f32_e32 v62, v62, v76
	v_mul_f32_e32 v63, v63, v77
	v_cvt_pk_bf16_f32 v69, v62, v63
	v_lshl_add_u64 v[62:63], v[72:73], 0, v[122:123]
	global_store_dwordx2 v[62:63], v[68:69], off
	v_lshlrev_b32_e32 v64, 16, v104
	v_and_b32_e32 v65, 0xffff0000, v104
	v_lshlrev_b32_e32 v72, 16, v105
	v_and_b32_e32 v73, 0xffff0000, v105
	v_mul_f32_e32 v58, v206, v58
	v_mul_f32_e32 v59, v207, v59
	v_mul_f32_e32 v58, v58, v64
	v_mul_f32_e32 v59, v59, v65
	v_cvt_pk_bf16_f32 v58, v58, v59
	v_mul_f32_e32 v59, v60, v16
	v_mul_f32_e32 v59, v208, v59
	v_mul_f32_e32 v60, v61, v16
	v_mul_f32_e32 v59, v59, v72
	v_mul_f32_e32 v60, v209, v60
	v_mul_f32_e32 v60, v60, v73
	v_cvt_pk_bf16_f32 v59, v59, v60
	global_store_dwordx2 v[62:63], v[58:59], off offset:32
	v_lshlrev_b32_e32 v64, 16, v94
	v_and_b32_e32 v65, 0xffff0000, v94
	v_lshlrev_b32_e32 v68, 16, v95
	v_and_b32_e32 v69, 0xffff0000, v95
	v_mul_f32_e32 v54, v54, v210
	v_mul_f32_e32 v55, v55, v211
	v_mul_f32_e32 v54, v54, v64
	v_mul_f32_e32 v55, v55, v65
	v_cvt_pk_bf16_f32 v54, v54, v55
	v_mul_f32_e32 v55, v56, v16
	v_mul_f32_e32 v55, v55, v212
	v_mul_f32_e32 v56, v57, v16
	v_mul_f32_e32 v55, v55, v68
	v_mul_f32_e32 v56, v56, v213
	v_mul_f32_e32 v56, v56, v69
	v_cvt_pk_bf16_f32 v55, v55, v56
	global_store_dwordx2 v[62:63], v[54:55], off offset:64
	v_lshlrev_b32_e32 v58, 16, v84
	v_and_b32_e32 v59, 0xffff0000, v84
	v_lshlrev_b32_e32 v60, 16, v85
	v_and_b32_e32 v61, 0xffff0000, v85
	v_mul_f32_e32 v50, v50, v214
	v_mul_f32_e32 v51, v51, v215
	v_mul_f32_e32 v50, v50, v58
	v_mul_f32_e32 v51, v51, v59
	v_cvt_pk_bf16_f32 v50, v50, v51
	v_mul_f32_e32 v51, v52, v16
	v_mul_f32_e32 v51, v51, v216
	v_mul_f32_e32 v16, v53, v16
	v_mul_f32_e32 v51, v51, v60
	v_mul_f32_e32 v16, v16, v217
	v_mul_f32_e32 v16, v16, v61
	v_cvt_pk_bf16_f32 v51, v51, v16
	global_store_dwordx2 v[62:63], v[50:51], off offset:96
	s_branch .LBB0_440
